# k15: k14 + grid barrier: L1 invalidate issued at arrival (overlaps the wait) instead of after the release
# speedup vs baseline: 1.0178x; 1.0123x over previous
; __device__ __forceinline__ unsigned xb_ld(unsigned* p)              { return __hip_atomic_load(p, __ATOMIC_RELAXED, __HIP_MEMORY_SCOPE_AGENT); }
; __device__ __forceinline__ unsigned xb_add(unsigned* p, unsigned v) { return __hip_atomic_fetch_add(p, v, __ATOMIC_RELAXED, __HIP_MEMORY_SCOPE_AGENT); }
; #define XB_SPIN(cond, bar) do { unsigned _sp = 0; while (cond) { __builtin_amdgcn_s_sleep(1); \
;     if ((++_sp & 255u) == 0u) { if (xb_ld(&(bar)[XB_TMO])) break; if (_sp > XB_SPIN_CAP) { atomicAdd(&(bar)[XB_TMO], 1u); break; } } } } while (0)
; __device__ __forceinline__ void xcd_barrier(const XcdBarrier& b) {
;     ...
;         const unsigned old = xb_add(&bar[XB_XSUB(b.x)], 1u);
;         const unsigned gen = old / nloc;
;         if (old + 1u == (gen + 1u) * nloc) {
;             __builtin_amdgcn_fence(__ATOMIC_RELEASE, "agent");
;             asm volatile("s_waitcnt vmcnt(0)" ::: "memory");
;             const unsigned og = xb_add(&bar[XB_TOP], 1u);
;             const unsigned tg = og / nx;
;             if (og + 1u == (tg + 1u) * nx) xb_add(&bar[XB_TOPGEN], 1u);
;             else XB_SPIN(xb_ld(&bar[XB_TOPGEN]) == tg, bar);
;             __builtin_amdgcn_fence(__ATOMIC_ACQUIRE, "agent");
;             xb_add(&bar[XB_XGEN(b.x)], 1u);
;             asm volatile("s_waitcnt vmcnt(0)" ::: "memory");
;         } else {
;             XB_SPIN(xb_ld(&bar[XB_XGEN(b.x)]) == gen, bar);
.LBB0_116:
	s_or_b64 exec, exec, s[8:9]
	v_cvt_f32_u32_e32 v5, v2
	s_waitcnt vmcnt(0)
	v_readfirstlane_b32 s6, v4
	v_sub_u32_e32 v4, 0, v2
	v_rcp_iflag_f32_e32 v5, v5
	v_add_u32_e32 v6, s6, v1
	v_mul_f32_e32 v5, 0x4f7ffffe, v5
	v_cvt_u32_f32_e32 v5, v5
	v_mul_lo_u32 v1, v4, v5
	v_mul_hi_u32 v1, v5, v1
	v_add_u32_e32 v1, v5, v1
	v_mul_hi_u32 v1, v6, v1
	v_mul_lo_u32 v4, v1, v2
	v_sub_u32_e32 v4, v6, v4
	v_add_u32_e32 v5, 1, v1
	v_sub_u32_e32 v7, v4, v2
	v_cmp_ge_u32_e32 vcc, v4, v2
	s_nop 1
	v_cndmask_b32_e32 v1, v1, v5, vcc
	v_cndmask_b32_e32 v4, v4, v7, vcc
	v_add_u32_e32 v5, 1, v1
	v_cmp_ge_u32_e32 vcc, v4, v2
	v_add_u32_e32 v4, 1, v6
	s_nop 0
	v_cndmask_b32_e32 v1, v1, v5, vcc
	v_mul_lo_u32 v5, v2, v1
	v_add_u32_e32 v2, v5, v2
	v_cmp_ne_u32_e32 vcc, v4, v2
	s_and_saveexec_b64 s[6:7], vcc
	s_xor_b64 s[6:7], exec, s[6:7]
	s_cbranch_execz .LBB0_130
	s_waitcnt lgkmcnt(0)
	buffer_inv sc1
	global_load_dword v0, v209, s[4:5] offset:1024 sc1
	s_add_u32 s10, s4, 0x2400
	s_addc_u32 s11, s5, 0
	s_waitcnt vmcnt(0)
	v_cmp_eq_u32_e32 vcc, v0, v1
	s_and_saveexec_b64 s[8:9], vcc
	s_cbranch_execz .LBB0_129
	s_mov_b32 s26, 1
	s_mov_b64 s[12:13], 0
	s_branch .LBB0_120

; __device__ __forceinline__ unsigned xb_ld(unsigned* p)              { return __hip_atomic_load(p, __ATOMIC_RELAXED, __HIP_MEMORY_SCOPE_AGENT); }
; #define XB_SPIN(cond, bar) do { unsigned _sp = 0; while (cond) { __builtin_amdgcn_s_sleep(1); \
;     if ((++_sp & 255u) == 0u) { if (xb_ld(&(bar)[XB_TMO])) break; if (_sp > XB_SPIN_CAP) { atomicAdd(&(bar)[XB_TMO], 1u); break; } } } } while (0)
; __device__ __forceinline__ void xcd_barrier(const XcdBarrier& b) {
;     ...
;             XB_SPIN(xb_ld(&bar[XB_XGEN(b.x)]) == gen, bar);
;             __builtin_amdgcn_fence(__ATOMIC_ACQUIRE, "agent");
;             asm volatile("s_waitcnt vmcnt(0)" ::: "memory");
.LBB0_129:
	s_or_b64 exec, exec, s[8:9]
	s_waitcnt vmcnt(0)
	s_waitcnt vmcnt(0)

; __device__ __forceinline__ unsigned xb_ld(unsigned* p)              { return __hip_atomic_load(p, __ATOMIC_RELAXED, __HIP_MEMORY_SCOPE_AGENT); }
; __device__ __forceinline__ unsigned xb_add(unsigned* p, unsigned v) { return __hip_atomic_fetch_add(p, v, __ATOMIC_RELAXED, __HIP_MEMORY_SCOPE_AGENT); }
; #define XB_SPIN(cond, bar) do { unsigned _sp = 0; while (cond) { __builtin_amdgcn_s_sleep(1); \
;     if ((++_sp & 255u) == 0u) { if (xb_ld(&(bar)[XB_TMO])) break; if (_sp > XB_SPIN_CAP) { atomicAdd(&(bar)[XB_TMO], 1u); break; } } } } while (0)
; __device__ __forceinline__ void xcd_barrier(const XcdBarrier& b) {
;     ...
;             const unsigned og = xb_add(&bar[XB_TOP], 1u);
;             const unsigned tg = og / nx;
;             if (og + 1u == (tg + 1u) * nx) xb_add(&bar[XB_TOPGEN], 1u);
;             else XB_SPIN(xb_ld(&bar[XB_TOPGEN]) == tg, bar);
;             __builtin_amdgcn_fence(__ATOMIC_ACQUIRE, "agent");
.LBB0_133:
	s_or_b64 exec, exec, s[8:9]
	buffer_inv sc1
	v_cvt_f32_u32_e32 v4, v0
	s_waitcnt vmcnt(0)
	v_readfirstlane_b32 s6, v2
	v_sub_u32_e32 v2, 0, v0
	s_mov_b64 s[8:9], -1
	v_rcp_iflag_f32_e32 v4, v4
	v_add_u32_e32 v1, s6, v1
	v_add_u32_e32 v5, 1, v1
	v_readlane_b32 s6, v251, 25
	v_mul_f32_e32 v4, 0x4f7ffffe, v4
	v_cvt_u32_f32_e32 v4, v4
	v_readlane_b32 s7, v251, 26
	v_mul_lo_u32 v2, v2, v4
	v_mul_hi_u32 v2, v4, v2
	v_add_u32_e32 v2, v4, v2
	v_mul_hi_u32 v2, v1, v2
	v_mul_lo_u32 v4, v2, v0
	v_sub_u32_e32 v1, v1, v4
	v_add_u32_e32 v6, 1, v2
	v_sub_u32_e32 v4, v1, v0
	v_cmp_ge_u32_e32 vcc, v1, v0
	s_nop 1
	v_cndmask_b32_e32 v2, v2, v6, vcc
	v_cndmask_b32_e32 v1, v1, v4, vcc
	v_add_u32_e32 v4, 1, v2
	v_cmp_ge_u32_e32 vcc, v1, v0
	s_nop 1
	v_cndmask_b32_e32 v2, v2, v4, vcc
	v_mul_lo_u32 v1, v0, v2
	v_add_u32_e32 v0, v1, v0
	v_cmp_ne_u32_e32 vcc, v5, v0
	v_mov_b64_e32 v[0:1], s[6:7]
	s_and_saveexec_b64 s[6:7], vcc
	s_cbranch_execz .LBB0_146
	v_readlane_b32 s8, v251, 25
	v_readlane_b32 s9, v251, 26
	s_mov_b64 s[10:11], 0
	s_nop 3
	global_load_dword v0, v3, s[8:9] sc1
	s_waitcnt vmcnt(0)
	v_cmp_eq_u32_e32 vcc, v0, v2
	s_and_saveexec_b64 s[8:9], vcc
	s_cbranch_execz .LBB0_145
	s_mov_b32 s24, 1
	s_branch .LBB0_137

; __device__ __forceinline__ unsigned xb_add(unsigned* p, unsigned v) { return __hip_atomic_fetch_add(p, v, __ATOMIC_RELAXED, __HIP_MEMORY_SCOPE_AGENT); }
; __device__ __forceinline__ void xcd_barrier(const XcdBarrier& b) {
;     ...
;             __builtin_amdgcn_fence(__ATOMIC_ACQUIRE, "agent");
;             xb_add(&bar[XB_XGEN(b.x)], 1u);
;             asm volatile("s_waitcnt vmcnt(0)" ::: "memory");
.LBB0_148:
	s_or_b64 exec, exec, s[6:7]
	s_mov_b64 s[6:7], exec
	v_mbcnt_lo_u32_b32 v0, s6, 0
	v_mbcnt_hi_u32_b32 v0, s7, v0
	v_cmp_eq_u32_e32 vcc, 0, v0
	s_waitcnt vmcnt(0)
	s_and_saveexec_b64 s[8:9], vcc
	s_cbranch_execz .LBB0_150
	s_bcnt1_i32_b64 s6, s[6:7]
	v_mov_b32_e32 v0, s6
	global_atomic_add v209, v0, s[4:5] offset:1024

; __device__ __forceinline__ unsigned xb_ld(unsigned* p)              { return __hip_atomic_load(p, __ATOMIC_RELAXED, __HIP_MEMORY_SCOPE_AGENT); }
; __device__ __forceinline__ unsigned xb_add(unsigned* p, unsigned v) { return __hip_atomic_fetch_add(p, v, __ATOMIC_RELAXED, __HIP_MEMORY_SCOPE_AGENT); }
; #define XB_SPIN(cond, bar) do { unsigned _sp = 0; while (cond) { __builtin_amdgcn_s_sleep(1); \
;     if ((++_sp & 255u) == 0u) { if (xb_ld(&(bar)[XB_TMO])) break; if (_sp > XB_SPIN_CAP) { atomicAdd(&(bar)[XB_TMO], 1u); break; } } } } while (0)
; __device__ __forceinline__ void xcd_barrier(const XcdBarrier& b) {
;     ...
;             const unsigned og = xb_add(&bar[XB_TOP], 1u);
;             const unsigned tg = og / nx;
;             if (og + 1u == (tg + 1u) * nx) xb_add(&bar[XB_TOPGEN], 1u);
;             else XB_SPIN(xb_ld(&bar[XB_TOPGEN]) == tg, bar);
;             __builtin_amdgcn_fence(__ATOMIC_ACQUIRE, "agent");
.LBB0_189:
	s_or_b64 exec, exec, s[8:9]
	buffer_inv sc1
	v_cvt_f32_u32_e32 v4, v0
	s_waitcnt vmcnt(0)
	v_readfirstlane_b32 s6, v2
	v_sub_u32_e32 v2, 0, v0
	s_mov_b64 s[8:9], -1
	v_rcp_iflag_f32_e32 v4, v4
	v_add_u32_e32 v1, s6, v1
	v_add_u32_e32 v5, 1, v1
	v_readlane_b32 s6, v251, 50
	v_mul_f32_e32 v4, 0x4f7ffffe, v4
	v_cvt_u32_f32_e32 v4, v4
	v_readlane_b32 s7, v251, 51
	v_mul_lo_u32 v2, v2, v4
	v_mul_hi_u32 v2, v4, v2
	v_add_u32_e32 v2, v4, v2
	v_mul_hi_u32 v2, v1, v2
	v_mul_lo_u32 v4, v2, v0
	v_sub_u32_e32 v1, v1, v4
	v_add_u32_e32 v6, 1, v2
	v_sub_u32_e32 v4, v1, v0
	v_cmp_ge_u32_e32 vcc, v1, v0
	s_nop 1
	v_cndmask_b32_e32 v2, v2, v6, vcc
	v_cndmask_b32_e32 v1, v1, v4, vcc
	v_add_u32_e32 v4, 1, v2
	v_cmp_ge_u32_e32 vcc, v1, v0
	s_nop 1
	v_cndmask_b32_e32 v2, v2, v4, vcc
	v_mul_lo_u32 v1, v0, v2
	v_add_u32_e32 v0, v1, v0
	v_cmp_ne_u32_e32 vcc, v5, v0
	v_mov_b64_e32 v[0:1], s[6:7]
	s_and_saveexec_b64 s[6:7], vcc
	s_cbranch_execz .LBB0_201
	v_readlane_b32 s8, v251, 50
	v_readlane_b32 s9, v251, 51
	s_mov_b64 s[10:11], 0
	s_nop 3
	global_load_dword v0, v3, s[8:9] sc1
	s_waitcnt vmcnt(0)
	v_cmp_eq_u32_e32 vcc, v0, v2
	s_and_saveexec_b64 s[8:9], vcc
	s_cbranch_execz .LBB0_200
	s_mov_b32 s24, 1
	s_branch .LBB0_193
